# retention part B: transposed-V reads as ds_read_b64 pairs on top of the gate-load hoist
# baseline (speedup 1.0000x reference)
; __device__ __forceinline__ unsigned pk2(float lo, float hi) { return f2bf(lo) | (f2bf(hi) << 16); }
; #define MFMA16(a, b, c) __builtin_amdgcn_mfma_f32_16x16x32_bf16(a, b, c, 0, 0, 0)
; __device__ __forceinline__ void ret2_task(const Params& p_, int l, int task, unsigned char* lds) {
;     ...
;       const int e = tid >> 3, d0 = (tid & 7) * 8; u32x4 o;
;       o.x = pk2(f0[0], f0[1]); o.y = pk2(f0[2], f0[3]); o.z = pk2(f1[0], f1[1]); o.w = pk2(f1[2], f1[3]); *(u32x4*)((bf16*)(lds + R_STF) + e * 72 + d0) = o;
;       o.x = pk2(g0[0], g0[1]); o.y = pk2(g0[2], g0[3]); o.z = pk2(g1[0], g1[1]); o.w = pk2(g1[2], g1[3]); *(u32x4*)((bf16*)(lds + R_STB) + e * 72 + d0) = o; }
;     __syncthreads();
;     const bf16* QS = (const bf16*)(lds + R_QS); const bf16* KS = (const bf16*)(lds + R_KS); const bf16* VT = (const bf16*)(lds + R_VT);
;     const bf16* STF = (const bf16*)(lds + R_STF); const bf16* STB = (const bf16*)(lds + R_STB);
;     bf16x8v qf[2];
; #pragma unroll
;     for (int ks = 0; ks < 2; ++ks) qf[ks] = *(const bf16x8v*)(QS + (16 * w + fr) * 72 + 32 * ks + 8 * fq);
;     const int ai = 16 * w + fr;
;     unsigned pp[8][2];
; #pragma unroll
;     for (int jt = 0; jt < 8; ++jt) { f32x4 acc = {0.f, 0.f, 0.f, 0.f};
; #pragma unroll
;         for (int ks = 0; ks < 2; ++ks) { const bf16x8v kf = *(const bf16x8v*)(KS + (16 * jt + fr) * 72 + 32 * ks + 8 * fq); acc = MFMA16(kf, qf[ks], acc); }
;         float sc[4];
; #pragma unroll
;         for (int r = 0; r < 4; ++r) { const int aj = 16 * jt + 4 * fq + r; const float wg = (aj <= ai) ? exp2f(l2f * (float)(ai - aj)) : exp2f(l2b * (float)(aj - ai)); sc[r] = acc[r] * wg; }
;         pp[jt][0] = pk2(sc[0], sc[1]); pp[jt][1] = pk2(sc[2], sc[3]); }
.LBB0_562:
	v_bfe_u32 v2, v4, 16, 1
	v_add3_u32 v2, v4, v2, s14
	v_bfe_u32 v3, v5, 16, 1
	v_lshrrev_b32_e32 v2, 16, v2
	v_add3_u32 v3, v5, v3, s14
	v_and_or_b32 v2, v3, s15, v2
	v_bfe_u32 v3, v6, 16, 1
	v_add3_u32 v3, v6, v3, s14
	v_bfe_u32 v4, v7, 16, 1
	v_lshrrev_b32_e32 v3, 16, v3
	v_add3_u32 v4, v7, v4, s14
	v_and_or_b32 v3, v4, s15, v3
	v_bfe_u32 v4, v8, 16, 1
	v_add3_u32 v4, v8, v4, s14
	v_bfe_u32 v5, v9, 16, 1
	v_lshrrev_b32_e32 v4, 16, v4
	v_add3_u32 v5, v9, v5, s14
	v_and_or_b32 v4, v5, s15, v4
	v_bfe_u32 v5, v10, 16, 1
	v_add3_u32 v5, v10, v5, s14
	v_bfe_u32 v6, v11, 16, 1
	v_lshrrev_b32_e32 v20, 3, v79
	v_and_b32_e32 v21, 56, v72
	v_lshrrev_b32_e32 v5, 16, v5
	v_add3_u32 v6, v11, v6, s14
	s_movk_i32 s39, 0x90
	v_and_or_b32 v5, v6, s15, v5
	v_mul_lo_u32 v6, v20, s39
	v_lshlrev_b32_e32 v7, 1, v21
	v_readlane_b32 s6, v255, 26
	s_add_i32 s24, 0, 0x18000
	v_bfe_u32 v0, v79, 4, 2
	v_add3_u32 v8, s6, v6, v7
	ds_write_b128 v8, v[2:5]
	v_bfe_u32 v2, v16, 16, 1
	v_add3_u32 v2, v16, v2, s14
	v_bfe_u32 v3, v17, 16, 1
	v_lshrrev_b32_e32 v2, 16, v2
	v_add3_u32 v3, v17, v3, s14
	v_and_or_b32 v2, v3, s15, v2
	v_bfe_u32 v3, v18, 16, 1
	v_add3_u32 v3, v18, v3, s14
	v_bfe_u32 v4, v19, 16, 1
	v_lshrrev_b32_e32 v3, 16, v3
	v_add3_u32 v4, v19, v4, s14
	v_and_or_b32 v3, v4, s15, v3
	v_bfe_u32 v4, v12, 16, 1
	v_add3_u32 v4, v12, v4, s14
	v_bfe_u32 v5, v13, 16, 1
	v_lshrrev_b32_e32 v4, 16, v4
	v_add3_u32 v5, v13, v5, s14
	v_and_or_b32 v4, v5, s15, v4
	v_bfe_u32 v5, v14, 16, 1
	v_add3_u32 v5, v14, v5, s14
	v_bfe_u32 v8, v15, 16, 1
	v_lshrrev_b32_e32 v5, 16, v5
	v_add3_u32 v8, v15, v8, s14
	v_and_or_b32 v5, v8, s15, v5
	v_add3_u32 v6, s24, v6, v7
	ds_write_b128 v6, v[2:5]
	v_ashrrev_i32_e32 v2, 2, v79
	v_lshlrev_b32_e32 v72, 4, v0
	v_and_b32_e32 v71, 15, v79
	v_bfi_b32 v70, -16, v2, v79
	v_add_u32_e32 v10, 0, v72
	v_mad_u64_u32 v[2:3], s[12:13], v70, s39, v[10:11]
	v_mad_u32_u24 v38, v71, s39, v10
	s_waitcnt lgkmcnt(0)
	s_barrier
	ds_read_b128 v[6:9], v2
	ds_read_b128 v[2:5], v2 offset:64
	ds_read_b128 v[10:13], v38 offset:18432
	ds_read_b128 v[80:83], v38 offset:34560
	ds_read_b128 v[14:17], v38 offset:18496
	ds_read_b128 v[18:21], v38 offset:20800
	s_waitcnt lgkmcnt(3)
	v_mfma_f32_16x16x32_bf16 v[10:13], v[10:13], v[6:9], 0
	v_lshlrev_b32_e32 v73, 2, v0
	v_cmp_gt_i32_e32 vcc, v73, v70
	v_or_b32_e32 v39, 0x60, v73
	s_waitcnt lgkmcnt(1)
	v_mfma_f32_16x16x32_bf16 v[10:13], v[14:17], v[2:5], v[10:13]
	v_sub_u32_e32 v14, v73, v70
	v_sub_u32_e32 v15, 0, v14
	v_max_i32_e32 v14, v14, v15
	v_cvt_f32_u32_e32 v14, v14
	v_cndmask_b32_e32 v15, v78, v75, vcc
	v_or_b32_e32 v74, 0x70, v73
	v_mfma_f32_16x16x32_bf16 v[80:83], v[80:83], v[6:9], 0
	v_mul_f32_e32 v16, v15, v14
	v_cmp_gt_f32_e32 vcc, s69, v16
	v_lshlrev_b32_e32 v0, 3, v0
	s_add_i32 s10, s10, s66
	v_cndmask_b32_e32 v16, 0, v183, vcc
	v_fmac_f32_e32 v16, v15, v14
	v_exp_f32_e32 v14, v16
	v_cndmask_b32_e32 v15, 0, v184, vcc
	v_cmp_lt_i32_e32 vcc, v73, v70
	s_add_i32 s3, s3, s66
	v_ldexp_f32 v42, v14, v15
	v_or_b32_e32 v14, 1, v73
	v_sub_u32_e32 v15, v14, v70
	v_sub_u32_e32 v14, v70, v14
	v_cndmask_b32_e32 v14, v15, v14, vcc
	v_cvt_f32_i32_e32 v14, v14
	v_cndmask_b32_e32 v15, v75, v78, vcc
	ds_read_b128 v[22:25], v38 offset:23104
	ds_read_b128 v[26:29], v38 offset:25408
	v_mul_f32_e32 v16, v15, v14
	v_cmp_gt_f32_e32 vcc, s69, v16
	ds_read_b128 v[30:33], v38 offset:27712
	ds_read_b128 v[34:37], v38 offset:30016
	v_cndmask_b32_e32 v16, 0, v183, vcc
	v_fmac_f32_e32 v16, v15, v14
	v_exp_f32_e32 v14, v16
	v_cndmask_b32_e32 v15, 0, v184, vcc
	ds_read_b128 v[66:69], v38 offset:32320
	v_ldexp_f32 v44, v14, v15
	v_or_b32_e32 v14, 2, v73
	v_cmp_gt_i32_e32 vcc, v14, v70
	v_sub_u32_e32 v14, v14, v70
	v_sub_u32_e32 v15, 0, v14
	v_max_i32_e32 v14, v14, v15
	v_cvt_f32_u32_e32 v14, v14
	v_cndmask_b32_e32 v15, v78, v75, vcc
	v_mul_f32_e32 v16, v15, v14
	v_cmp_gt_f32_e32 vcc, s69, v16
	s_nop 1
	v_cndmask_b32_e32 v16, 0, v183, vcc
	v_fmac_f32_e32 v16, v15, v14
	v_exp_f32_e32 v14, v16
	v_cndmask_b32_e32 v15, 0, v184, vcc
	v_ldexp_f32 v43, v14, v15
	v_or_b32_e32 v14, 3, v73
	v_cmp_gt_i32_e32 vcc, v14, v70
	v_sub_u32_e32 v14, v14, v70
	v_sub_u32_e32 v15, 0, v14
	v_max_i32_e32 v14, v14, v15
	v_cvt_f32_u32_e32 v14, v14
	v_cndmask_b32_e32 v15, v78, v75, vcc
	v_mul_f32_e32 v16, v15, v14
	v_cmp_gt_f32_e32 vcc, s69, v16
	s_nop 1
	v_cndmask_b32_e32 v16, 0, v183, vcc
	v_fmac_f32_e32 v16, v15, v14
	v_exp_f32_e32 v14, v16
	v_cndmask_b32_e32 v15, 0, v184, vcc
	v_ldexp_f32 v45, v14, v15
	ds_read_b128 v[14:17], v38 offset:20736
	s_waitcnt lgkmcnt(0)
	v_mfma_f32_16x16x32_bf16 v[14:17], v[14:17], v[6:9], 0
	v_mfma_f32_16x16x32_bf16 v[14:17], v[18:21], v[2:5], v[14:17]
	v_or_b32_e32 v18, 16, v73
	v_cmp_gt_i32_e32 vcc, v18, v70
	v_sub_u32_e32 v18, v18, v70
	v_sub_u32_e32 v19, 0, v18
	v_max_i32_e32 v18, v18, v19
	v_cvt_f32_u32_e32 v18, v18
	v_cndmask_b32_e32 v19, v78, v75, vcc
	v_mul_f32_e32 v20, v19, v18
	v_cmp_gt_f32_e32 vcc, s69, v20
	s_nop 1
	v_cndmask_b32_e32 v20, 0, v183, vcc
	v_fmac_f32_e32 v20, v19, v18
	v_exp_f32_e32 v18, v20
	v_cndmask_b32_e32 v19, 0, v184, vcc
	v_ldexp_f32 v46, v18, v19
	v_or_b32_e32 v18, 17, v73
	v_cmp_gt_i32_e32 vcc, v18, v70
	v_sub_u32_e32 v18, v18, v70
	v_sub_u32_e32 v19, 0, v18
	v_max_i32_e32 v18, v18, v19
	v_cvt_f32_u32_e32 v18, v18
	v_cndmask_b32_e32 v19, v78, v75, vcc
	v_mul_f32_e32 v20, v19, v18
	v_cmp_gt_f32_e32 vcc, s69, v20
	s_nop 1
	v_cndmask_b32_e32 v20, 0, v183, vcc
	v_fmac_f32_e32 v20, v19, v18
	v_exp_f32_e32 v18, v20
	v_cndmask_b32_e32 v19, 0, v184, vcc
	v_ldexp_f32 v48, v18, v19
	v_or_b32_e32 v18, 18, v73
	v_cmp_gt_i32_e32 vcc, v18, v70
	v_sub_u32_e32 v18, v18, v70
	v_sub_u32_e32 v19, 0, v18
	v_max_i32_e32 v18, v18, v19
	v_cvt_f32_u32_e32 v18, v18
	v_cndmask_b32_e32 v19, v78, v75, vcc
	v_mul_f32_e32 v20, v19, v18
	v_cmp_gt_f32_e32 vcc, s69, v20
	s_nop 1
	v_cndmask_b32_e32 v20, 0, v183, vcc
	v_fmac_f32_e32 v20, v19, v18
	v_exp_f32_e32 v18, v20
	v_cndmask_b32_e32 v19, 0, v184, vcc
	v_ldexp_f32 v47, v18, v19
	v_or_b32_e32 v18, 19, v73
	v_cmp_gt_i32_e32 vcc, v18, v70
	v_sub_u32_e32 v18, v18, v70
	v_sub_u32_e32 v19, 0, v18
	v_max_i32_e32 v18, v18, v19
	v_cvt_f32_u32_e32 v18, v18
	v_cndmask_b32_e32 v19, v78, v75, vcc
	v_mul_f32_e32 v20, v19, v18
	v_cmp_gt_f32_e32 vcc, s69, v20
	s_nop 1
	v_cndmask_b32_e32 v20, 0, v183, vcc
	v_fmac_f32_e32 v20, v19, v18
	v_exp_f32_e32 v18, v20
	v_cndmask_b32_e32 v19, 0, v184, vcc
	v_ldexp_f32 v49, v18, v19
	ds_read_b128 v[18:21], v38 offset:23040
	s_waitcnt lgkmcnt(0)
; __device__ __forceinline__ unsigned pk2(float lo, float hi) { return f2bf(lo) | (f2bf(hi) << 16); }
; #define MFMA16(a, b, c) __builtin_amdgcn_mfma_f32_16x16x32_bf16(a, b, c, 0, 0, 0)
; __device__ __forceinline__ void ret2_task(const Params& p_, int l, int task, unsigned char* lds) {
;     ...
;     for (int jt = 0; jt < 8; ++jt) { f32x4 acc = {0.f, 0.f, 0.f, 0.f};
; #pragma unroll
;         for (int ks = 0; ks < 2; ++ks) { const bf16x8v kf = *(const bf16x8v*)(KS + (16 * jt + fr) * 72 + 32 * ks + 8 * fq); acc = MFMA16(kf, qf[ks], acc); }
;         float sc[4];
; #pragma unroll
;         for (int r = 0; r < 4; ++r) { const int aj = 16 * jt + 4 * fq + r; const float wg = (aj <= ai) ? exp2f(l2f * (float)(ai - aj)) : exp2f(l2b * (float)(aj - ai)); sc[r] = acc[r] * wg; }
;         pp[jt][0] = pk2(sc[0], sc[1]); pp[jt][1] = pk2(sc[2], sc[3]); }
	v_mfma_f32_16x16x32_bf16 v[18:21], v[18:21], v[6:9], 0
	v_mfma_f32_16x16x32_bf16 v[18:21], v[22:25], v[2:5], v[18:21]
	v_or_b32_e32 v22, 32, v73
	v_cmp_gt_i32_e32 vcc, v22, v70
	v_sub_u32_e32 v22, v22, v70
	v_sub_u32_e32 v23, 0, v22
	v_max_i32_e32 v22, v22, v23
	v_cvt_f32_u32_e32 v22, v22
	v_cndmask_b32_e32 v23, v78, v75, vcc
	v_mul_f32_e32 v24, v23, v22
	v_cmp_gt_f32_e32 vcc, s69, v24
	s_nop 1
	v_cndmask_b32_e32 v24, 0, v183, vcc
	v_fmac_f32_e32 v24, v23, v22
	v_exp_f32_e32 v22, v24
	v_cndmask_b32_e32 v23, 0, v184, vcc
	v_ldexp_f32 v50, v22, v23
	v_or_b32_e32 v22, 33, v73
	v_cmp_gt_i32_e32 vcc, v22, v70
	v_sub_u32_e32 v22, v22, v70
	v_sub_u32_e32 v23, 0, v22
	v_max_i32_e32 v22, v22, v23
	v_cvt_f32_u32_e32 v22, v22
	v_cndmask_b32_e32 v23, v78, v75, vcc
	v_mul_f32_e32 v24, v23, v22
	v_cmp_gt_f32_e32 vcc, s69, v24
	s_nop 1
	v_cndmask_b32_e32 v24, 0, v183, vcc
	v_fmac_f32_e32 v24, v23, v22
	v_exp_f32_e32 v22, v24
	v_cndmask_b32_e32 v23, 0, v184, vcc
	v_ldexp_f32 v52, v22, v23
	v_or_b32_e32 v22, 34, v73
	v_cmp_gt_i32_e32 vcc, v22, v70
	v_sub_u32_e32 v22, v22, v70
	v_sub_u32_e32 v23, 0, v22
	v_max_i32_e32 v22, v22, v23
	v_cvt_f32_u32_e32 v22, v22
	v_cndmask_b32_e32 v23, v78, v75, vcc
	v_mul_f32_e32 v24, v23, v22
	v_cmp_gt_f32_e32 vcc, s69, v24
	s_nop 1
	v_cndmask_b32_e32 v24, 0, v183, vcc
	v_fmac_f32_e32 v24, v23, v22
	v_exp_f32_e32 v22, v24
	v_cndmask_b32_e32 v23, 0, v184, vcc
	v_ldexp_f32 v51, v22, v23
	v_or_b32_e32 v22, 35, v73
	v_cmp_gt_i32_e32 vcc, v22, v70
	v_sub_u32_e32 v22, v22, v70
	v_sub_u32_e32 v23, 0, v22
	v_max_i32_e32 v22, v22, v23
	v_cvt_f32_u32_e32 v22, v22
	v_cndmask_b32_e32 v23, v78, v75, vcc
	v_mul_f32_e32 v24, v23, v22
	v_cmp_gt_f32_e32 vcc, s69, v24
	s_nop 1
	v_cndmask_b32_e32 v24, 0, v183, vcc
	v_fmac_f32_e32 v24, v23, v22
	v_exp_f32_e32 v22, v24
	v_cndmask_b32_e32 v23, 0, v184, vcc
	v_ldexp_f32 v53, v22, v23
	ds_read_b128 v[22:25], v38 offset:25344
	s_waitcnt lgkmcnt(0)
	v_mfma_f32_16x16x32_bf16 v[22:25], v[22:25], v[6:9], 0
	v_mfma_f32_16x16x32_bf16 v[22:25], v[26:29], v[2:5], v[22:25]
	v_or_b32_e32 v26, 48, v73
	v_cmp_gt_i32_e32 vcc, v26, v70
	v_sub_u32_e32 v26, v26, v70
	v_sub_u32_e32 v27, 0, v26
	v_max_i32_e32 v26, v26, v27
	v_cvt_f32_u32_e32 v26, v26
	v_cndmask_b32_e32 v27, v78, v75, vcc
	v_mul_f32_e32 v28, v27, v26
	v_cmp_gt_f32_e32 vcc, s69, v28
	s_nop 1
	v_cndmask_b32_e32 v28, 0, v183, vcc
	v_fmac_f32_e32 v28, v27, v26
	v_exp_f32_e32 v26, v28
	v_cndmask_b32_e32 v27, 0, v184, vcc
	v_ldexp_f32 v54, v26, v27
	v_or_b32_e32 v26, 49, v73
	v_cmp_gt_i32_e32 vcc, v26, v70
	v_sub_u32_e32 v26, v26, v70
	v_sub_u32_e32 v27, 0, v26
	v_max_i32_e32 v26, v26, v27
	v_cvt_f32_u32_e32 v26, v26
	v_cndmask_b32_e32 v27, v78, v75, vcc
	v_mul_f32_e32 v28, v27, v26
	v_cmp_gt_f32_e32 vcc, s69, v28
	s_nop 1
	v_cndmask_b32_e32 v28, 0, v183, vcc
	v_fmac_f32_e32 v28, v27, v26
	v_exp_f32_e32 v26, v28
	v_cndmask_b32_e32 v27, 0, v184, vcc
	v_ldexp_f32 v56, v26, v27
	v_or_b32_e32 v26, 50, v73
	v_cmp_gt_i32_e32 vcc, v26, v70
	v_sub_u32_e32 v26, v26, v70
	v_sub_u32_e32 v27, 0, v26
	v_max_i32_e32 v26, v26, v27
	v_cvt_f32_u32_e32 v26, v26
	v_cndmask_b32_e32 v27, v78, v75, vcc
	v_mul_f32_e32 v28, v27, v26
	v_cmp_gt_f32_e32 vcc, s69, v28
	s_nop 1
	v_cndmask_b32_e32 v28, 0, v183, vcc
	v_fmac_f32_e32 v28, v27, v26
	v_exp_f32_e32 v26, v28
	v_cndmask_b32_e32 v27, 0, v184, vcc
	v_ldexp_f32 v55, v26, v27
	v_or_b32_e32 v26, 51, v73
	v_cmp_gt_i32_e32 vcc, v26, v70
	v_sub_u32_e32 v26, v26, v70
	v_sub_u32_e32 v27, 0, v26
	v_max_i32_e32 v26, v26, v27
	v_cvt_f32_u32_e32 v26, v26
	v_cndmask_b32_e32 v27, v78, v75, vcc
	v_mul_f32_e32 v28, v27, v26
	v_cmp_gt_f32_e32 vcc, s69, v28
	s_nop 1
	v_cndmask_b32_e32 v28, 0, v183, vcc
	v_fmac_f32_e32 v28, v27, v26
	v_exp_f32_e32 v26, v28
	v_cndmask_b32_e32 v27, 0, v184, vcc
	v_ldexp_f32 v57, v26, v27
	ds_read_b128 v[26:29], v38 offset:27648
	s_waitcnt lgkmcnt(0)
	v_mfma_f32_16x16x32_bf16 v[26:29], v[26:29], v[6:9], 0
	v_mfma_f32_16x16x32_bf16 v[26:29], v[30:33], v[2:5], v[26:29]
	v_or_b32_e32 v30, 64, v73
	v_cmp_gt_i32_e32 vcc, v30, v70
	v_sub_u32_e32 v30, v30, v70
	v_sub_u32_e32 v31, 0, v30
	v_max_i32_e32 v30, v30, v31
	v_cvt_f32_u32_e32 v30, v30
	v_cndmask_b32_e32 v31, v78, v75, vcc
	v_mul_f32_e32 v32, v31, v30
	v_cmp_gt_f32_e32 vcc, s69, v32
	s_nop 1
	v_cndmask_b32_e32 v32, 0, v183, vcc
	v_fmac_f32_e32 v32, v31, v30
	v_exp_f32_e32 v30, v32
	v_cndmask_b32_e32 v31, 0, v184, vcc
	v_ldexp_f32 v58, v30, v31
	v_or_b32_e32 v30, 0x41, v73
	v_cmp_gt_i32_e32 vcc, v30, v70
	v_sub_u32_e32 v30, v30, v70
	v_sub_u32_e32 v31, 0, v30
	v_max_i32_e32 v30, v30, v31
	v_cvt_f32_u32_e32 v30, v30
	v_cndmask_b32_e32 v31, v78, v75, vcc
	v_mul_f32_e32 v32, v31, v30
	v_cmp_gt_f32_e32 vcc, s69, v32
	s_nop 1
	v_cndmask_b32_e32 v32, 0, v183, vcc
	v_fmac_f32_e32 v32, v31, v30
	v_exp_f32_e32 v30, v32
	v_cndmask_b32_e32 v31, 0, v184, vcc
	v_ldexp_f32 v60, v30, v31
	v_or_b32_e32 v30, 0x42, v73
	v_cmp_gt_i32_e32 vcc, v30, v70
	v_sub_u32_e32 v30, v30, v70
	v_sub_u32_e32 v31, 0, v30
	v_max_i32_e32 v30, v30, v31
	v_cvt_f32_u32_e32 v30, v30
	v_cndmask_b32_e32 v31, v78, v75, vcc
	v_mul_f32_e32 v32, v31, v30
	v_cmp_gt_f32_e32 vcc, s69, v32
	s_nop 1
	v_cndmask_b32_e32 v32, 0, v183, vcc
	v_fmac_f32_e32 v32, v31, v30
	v_exp_f32_e32 v30, v32
	v_cndmask_b32_e32 v31, 0, v184, vcc
	v_ldexp_f32 v59, v30, v31
	v_or_b32_e32 v30, 0x43, v73
	v_cmp_gt_i32_e32 vcc, v30, v70
	v_sub_u32_e32 v30, v30, v70
	v_sub_u32_e32 v31, 0, v30
	v_max_i32_e32 v30, v30, v31
	v_cvt_f32_u32_e32 v30, v30
	v_cndmask_b32_e32 v31, v78, v75, vcc
	v_mul_f32_e32 v32, v31, v30
	v_cmp_gt_f32_e32 vcc, s69, v32
	s_nop 1
	v_cndmask_b32_e32 v32, 0, v183, vcc
	v_fmac_f32_e32 v32, v31, v30
	v_exp_f32_e32 v30, v32
	v_cndmask_b32_e32 v31, 0, v184, vcc
	v_ldexp_f32 v61, v30, v31
	ds_read_b128 v[30:33], v38 offset:29952
	s_waitcnt lgkmcnt(0)
; __device__ __forceinline__ unsigned pk2(float lo, float hi) { return f2bf(lo) | (f2bf(hi) << 16); }
; #define MFMA16(a, b, c) __builtin_amdgcn_mfma_f32_16x16x32_bf16(a, b, c, 0, 0, 0)
; __device__ __forceinline__ void ret2_task(const Params& p_, int l, int task, unsigned char* lds) {
;     ...
;     for (int jt = 0; jt < 8; ++jt) { f32x4 acc = {0.f, 0.f, 0.f, 0.f};
; #pragma unroll
;         for (int ks = 0; ks < 2; ++ks) { const bf16x8v kf = *(const bf16x8v*)(KS + (16 * jt + fr) * 72 + 32 * ks + 8 * fq); acc = MFMA16(kf, qf[ks], acc); }
;         float sc[4];
; #pragma unroll
;         for (int r = 0; r < 4; ++r) { const int aj = 16 * jt + 4 * fq + r; const float wg = (aj <= ai) ? exp2f(l2f * (float)(ai - aj)) : exp2f(l2b * (float)(aj - ai)); sc[r] = acc[r] * wg; }
;         pp[jt][0] = pk2(sc[0], sc[1]); pp[jt][1] = pk2(sc[2], sc[3]); }
;     const float qdf = exp2f(l2f * (float)(ai + 1)), qdb = exp2f(l2b * (float)(128 - ai));
	v_mfma_f32_16x16x32_bf16 v[30:33], v[30:33], v[6:9], 0
	v_mfma_f32_16x16x32_bf16 v[30:33], v[34:37], v[2:5], v[30:33]
	v_or_b32_e32 v34, 0x50, v73
	v_cmp_gt_i32_e32 vcc, v34, v70
	v_sub_u32_e32 v34, v34, v70
	v_sub_u32_e32 v35, 0, v34
	v_max_i32_e32 v34, v34, v35
	v_cvt_f32_u32_e32 v34, v34
	v_cndmask_b32_e32 v35, v78, v75, vcc
	v_mul_f32_e32 v36, v35, v34
	v_cmp_gt_f32_e32 vcc, s69, v36
	s_nop 1
	v_cndmask_b32_e32 v36, 0, v183, vcc
	v_fmac_f32_e32 v36, v35, v34
	v_exp_f32_e32 v34, v36
	v_cndmask_b32_e32 v35, 0, v184, vcc
	v_ldexp_f32 v62, v34, v35
	v_or_b32_e32 v34, 0x51, v73
	v_cmp_gt_i32_e32 vcc, v34, v70
	v_sub_u32_e32 v34, v34, v70
	v_sub_u32_e32 v35, 0, v34
	v_max_i32_e32 v34, v34, v35
	v_cvt_f32_u32_e32 v34, v34
	v_cndmask_b32_e32 v35, v78, v75, vcc
	v_mul_f32_e32 v36, v35, v34
	v_cmp_gt_f32_e32 vcc, s69, v36
	s_nop 1
	v_cndmask_b32_e32 v36, 0, v183, vcc
	v_fmac_f32_e32 v36, v35, v34
	v_exp_f32_e32 v34, v36
	v_cndmask_b32_e32 v35, 0, v184, vcc
	v_ldexp_f32 v64, v34, v35
	v_or_b32_e32 v34, 0x52, v73
	v_cmp_gt_i32_e32 vcc, v34, v70
	v_sub_u32_e32 v34, v34, v70
	v_sub_u32_e32 v35, 0, v34
	v_max_i32_e32 v34, v34, v35
	v_cvt_f32_u32_e32 v34, v34
	v_cndmask_b32_e32 v35, v78, v75, vcc
	v_mul_f32_e32 v36, v35, v34
	v_cmp_gt_f32_e32 vcc, s69, v36
	s_nop 1
	v_cndmask_b32_e32 v36, 0, v183, vcc
	v_fmac_f32_e32 v36, v35, v34
	v_exp_f32_e32 v34, v36
	v_cndmask_b32_e32 v35, 0, v184, vcc
	v_ldexp_f32 v63, v34, v35
	v_or_b32_e32 v34, 0x53, v73
	v_cmp_gt_i32_e32 vcc, v34, v70
	v_sub_u32_e32 v34, v34, v70
	v_sub_u32_e32 v35, 0, v34
	v_max_i32_e32 v34, v34, v35
	v_cvt_f32_u32_e32 v34, v34
	v_cndmask_b32_e32 v35, v78, v75, vcc
	v_mul_f32_e32 v36, v35, v34
	v_cmp_gt_f32_e32 vcc, s69, v36
	s_nop 1
	v_cndmask_b32_e32 v36, 0, v183, vcc
	v_fmac_f32_e32 v36, v35, v34
	v_exp_f32_e32 v34, v36
	v_cndmask_b32_e32 v35, 0, v184, vcc
	v_cmp_gt_i32_e32 vcc, v39, v70
	v_sub_u32_e32 v39, v39, v70
	v_sub_u32_e32 v40, 0, v39
	v_ldexp_f32 v65, v34, v35
	ds_read_b128 v[34:37], v38 offset:32256
	v_max_i32_e32 v39, v39, v40
	v_cvt_f32_u32_e32 v39, v39
	v_cndmask_b32_e32 v40, v78, v75, vcc
	s_waitcnt lgkmcnt(0)
	v_mfma_f32_16x16x32_bf16 v[34:37], v[34:37], v[6:9], 0
	v_mul_f32_e32 v41, v40, v39
	v_cmp_gt_f32_e32 vcc, s69, v41
	v_mfma_f32_16x16x32_bf16 v[34:37], v[66:69], v[2:5], v[34:37]
	s_nop 0
	v_cndmask_b32_e32 v41, 0, v183, vcc
	v_fmac_f32_e32 v41, v40, v39
	v_exp_f32_e32 v39, v41
	v_cndmask_b32_e32 v40, 0, v184, vcc
	v_ldexp_f32 v66, v39, v40
	v_or_b32_e32 v39, 0x61, v73
	v_cmp_gt_i32_e32 vcc, v39, v70
	v_sub_u32_e32 v39, v39, v70
	v_sub_u32_e32 v40, 0, v39
	v_max_i32_e32 v39, v39, v40
	v_cvt_f32_u32_e32 v39, v39
	v_cndmask_b32_e32 v40, v78, v75, vcc
	v_mul_f32_e32 v41, v40, v39
	v_cmp_gt_f32_e32 vcc, s69, v41
	s_nop 1
	v_cndmask_b32_e32 v41, 0, v183, vcc
	v_fmac_f32_e32 v41, v40, v39
	v_exp_f32_e32 v39, v41
	v_cndmask_b32_e32 v40, 0, v184, vcc
	v_ldexp_f32 v68, v39, v40
	v_or_b32_e32 v39, 0x62, v73
	v_cmp_gt_i32_e32 vcc, v39, v70
	v_sub_u32_e32 v39, v39, v70
	v_sub_u32_e32 v40, 0, v39
	v_max_i32_e32 v39, v39, v40
	v_cvt_f32_u32_e32 v39, v39
	v_cndmask_b32_e32 v40, v78, v75, vcc
	v_mul_f32_e32 v41, v40, v39
	v_cmp_gt_f32_e32 vcc, s69, v41
	s_nop 1
	v_cndmask_b32_e32 v41, 0, v183, vcc
	v_fmac_f32_e32 v41, v40, v39
	v_exp_f32_e32 v39, v41
	v_cndmask_b32_e32 v40, 0, v184, vcc
	v_ldexp_f32 v67, v39, v40
	v_or_b32_e32 v39, 0x63, v73
	v_cmp_gt_i32_e32 vcc, v39, v70
	v_sub_u32_e32 v39, v39, v70
	v_sub_u32_e32 v40, 0, v39
	v_max_i32_e32 v39, v39, v40
	v_cvt_f32_u32_e32 v39, v39
	v_cndmask_b32_e32 v40, v78, v75, vcc
	v_mul_f32_e32 v41, v40, v39
	v_cmp_gt_f32_e32 vcc, s69, v41
	s_nop 1
	v_cndmask_b32_e32 v41, 0, v183, vcc
	v_fmac_f32_e32 v41, v40, v39
	v_cndmask_b32_e32 v40, 0, v184, vcc
	v_cmp_gt_i32_e32 vcc, v74, v70
	v_sub_u32_e32 v74, v74, v70
	v_sub_u32_e32 v76, 0, v74
	v_max_i32_e32 v74, v74, v76
	v_cvt_f32_u32_e32 v74, v74
	v_cndmask_b32_e32 v76, v78, v75, vcc
	v_exp_f32_e32 v39, v41
	v_mul_f32_e32 v77, v76, v74
	v_cmp_gt_f32_e32 vcc, s69, v77
	v_ldexp_f32 v69, v39, v40
	ds_read_b128 v[38:41], v38 offset:34624
	v_cndmask_b32_e32 v77, 0, v183, vcc
	v_fmac_f32_e32 v77, v76, v74
	v_exp_f32_e32 v74, v77
	v_cndmask_b32_e32 v76, 0, v184, vcc
	s_waitcnt lgkmcnt(0)
	v_mfma_f32_16x16x32_bf16 v[38:41], v[38:41], v[2:5], v[80:83]
	v_ldexp_f32 v76, v74, v76
	v_or_b32_e32 v74, 0x71, v73
	v_cmp_gt_i32_e32 vcc, v74, v70
	v_sub_u32_e32 v74, v74, v70
	v_sub_u32_e32 v77, 0, v74
	v_max_i32_e32 v74, v74, v77
	v_cvt_f32_u32_e32 v74, v74
	v_cndmask_b32_e32 v77, v78, v75, vcc
	v_mov_b32_e32 v82, v35
	v_mov_b32_e32 v35, v36
	v_mul_f32_e32 v79, v77, v74
	v_cmp_gt_f32_e32 vcc, s69, v79
	v_mov_b32_e32 v36, v31
	v_mov_b32_e32 v31, v32
	v_cndmask_b32_e32 v79, 0, v183, vcc
	v_fmac_f32_e32 v79, v77, v74
	v_exp_f32_e32 v74, v79
	v_cndmask_b32_e32 v77, 0, v184, vcc
	v_mov_b32_e32 v32, v27
	v_mov_b32_e32 v27, v28
	v_ldexp_f32 v80, v74, v77
	v_or_b32_e32 v74, 0x72, v73
	v_cmp_gt_i32_e32 vcc, v74, v70
	v_sub_u32_e32 v74, v74, v70
	v_sub_u32_e32 v77, 0, v74
	v_max_i32_e32 v74, v74, v77
	v_cvt_f32_u32_e32 v74, v74
	v_cndmask_b32_e32 v77, v78, v75, vcc
	v_or_b32_e32 v73, 0x73, v73
	v_pk_mul_f32 v[58:59], v[58:59], v[26:27]
	v_mul_f32_e32 v79, v77, v74
	v_cmp_gt_f32_e32 vcc, s69, v79
	v_mov_b32_e32 v26, v23
	v_mov_b32_e32 v23, v24
	v_cndmask_b32_e32 v79, 0, v183, vcc
	v_fmac_f32_e32 v79, v77, v74
	v_exp_f32_e32 v74, v79
	v_cndmask_b32_e32 v77, 0, v184, vcc
	v_cmp_gt_i32_e32 vcc, v73, v70
	v_sub_u32_e32 v73, v73, v70
	v_ldexp_f32 v77, v74, v77
	v_sub_u32_e32 v74, 0, v73
	v_mov_b32_e32 v83, v37
	v_mov_b32_e32 v37, v33
	v_mov_b32_e32 v33, v29
	v_pk_mul_f32 v[28:29], v[54:55], v[22:23]
	v_mov_b32_e32 v22, v19
; __device__ __forceinline__ unsigned pk2(float lo, float hi) { return f2bf(lo) | (f2bf(hi) << 16); }
; #define MFMA16(a, b, c) __builtin_amdgcn_mfma_f32_16x16x32_bf16(a, b, c, 0, 0, 0)
; __device__ __forceinline__ void ret2_task(const Params& p_, int l, int task, unsigned char* lds) {
;     ...
;         pp[jt][0] = pk2(sc[0], sc[1]); pp[jt][1] = pk2(sc[2], sc[3]); }
;     const float qdf = exp2f(l2f * (float)(ai + 1)), qdb = exp2f(l2b * (float)(128 - ai));
;     f32x4 tot[4]; float ss = 0.f;
; #pragma unroll
;     for (int et = 0; et < 4; ++et) { f32x4 o = {0.f, 0.f, 0.f, 0.f}, cfa = o, cba = o;
; #pragma unroll
;         for (int t = 0; t < 4; ++t) { const u32x2 vlo = *(const u32x2*)(VT + (16 * et + fr) * 136 + 32 * t + 4 * fq), vhi = *(const u32x2*)(VT + (16 * et + fr) * 136 + 32 * t + 16 + 4 * fq);
;             o = MFMA16(mk8(vlo.x, vlo.y, vhi.x, vhi.y), mk8(pp[2 * t][0], pp[2 * t][1], pp[2 * t + 1][0], pp[2 * t + 1][1]), o); }
	v_mov_b32_e32 v19, v20
	v_max_i32_e32 v73, v73, v74
	v_pk_mul_f32 v[50:51], v[50:51], v[18:19]
	v_mov_b32_e32 v18, v15
	v_mov_b32_e32 v15, v16
	v_cvt_f32_u32_e32 v73, v73
	v_mov_b32_e32 v23, v21
	v_pk_mul_f32 v[20:21], v[46:47], v[14:15]
	v_mov_b32_e32 v14, v11
	v_mov_b32_e32 v15, v13
	v_mov_b32_e32 v11, v12
	v_mov_b32_e32 v12, v38
	v_mov_b32_e32 v13, v40
	v_pk_mul_f32 v[10:11], v[42:43], v[10:11]
	v_pk_mul_f32 v[42:43], v[76:77], v[12:13]
	v_add_u32_e32 v12, 1, v70
	v_cvt_f32_i32_e32 v12, v12
	v_cndmask_b32_e32 v74, v78, v75, vcc
	v_mul_f32_e32 v79, v74, v73
	v_cmp_gt_f32_e32 vcc, s69, v79
	v_mul_f32_e32 v13, v78, v12
	v_mov_b32_e32 v40, v39
	v_cndmask_b32_e32 v79, 0, v183, vcc
	v_fmac_f32_e32 v79, v74, v73
	v_cndmask_b32_e32 v74, 0, v184, vcc
	v_cmp_gt_f32_e32 vcc, s69, v13
	v_exp_f32_e32 v73, v79
	v_pk_mul_f32 v[52:53], v[52:53], v[22:23]
	v_cndmask_b32_e32 v13, 0, v183, vcc
	v_fmac_f32_e32 v13, v78, v12
	v_exp_f32_e32 v12, v13
	v_cndmask_b32_e32 v13, 0, v184, vcc
	v_ldexp_f32 v81, v73, v74
	v_pk_mul_f32 v[22:23], v[44:45], v[14:15]
	v_ldexp_f32 v38, v12, v13
	v_sub_u32_e32 v12, 0x80, v70
	v_cvt_f32_i32_e32 v12, v12
	v_pk_mul_f32 v[44:45], v[80:81], v[40:41]
	v_mov_b32_e32 v19, v17
	v_pk_mul_f32 v[18:19], v[48:49], v[18:19]
	v_mul_f32_e32 v13, v75, v12
	v_cmp_gt_f32_e32 vcc, s69, v13
	v_mov_b32_e32 v27, v25
	v_bfe_u32 v24, v23, 16, 1
	v_cndmask_b32_e32 v13, 0, v183, vcc
	v_fmac_f32_e32 v13, v75, v12
	v_exp_f32_e32 v12, v13
	v_cndmask_b32_e32 v13, 0, v184, vcc
	v_bfe_u32 v25, v22, 16, 1
	v_add3_u32 v22, v22, v25, s14
	v_ldexp_f32 v40, v12, v13
	v_mul_u32_u24_e32 v12, 0x110, v71
	v_add3_u32 v39, 0, v12, v0
	v_add_u32_e32 v41, 0x9000, v39
	ds_read_b64 v[14:15], v41
	ds_read_b64 v[16:17], v41 offset:32
	v_bfe_u32 v12, v19, 16, 1
	v_bfe_u32 v13, v18, 16, 1
	v_add3_u32 v18, v18, v13, s14
	v_add3_u32 v12, v19, v12, s14
	v_bfe_u32 v13, v10, 16, 1
	v_bfe_u32 v19, v11, 16, 1
	v_add3_u32 v11, v11, v19, s14
	v_add3_u32 v10, v10, v13, s14
	v_add3_u32 v23, v23, v24, s14
	v_bfe_u32 v24, v20, 16, 1
	v_bfe_u32 v25, v21, 16, 1
	v_lshrrev_b32_e32 v10, 16, v10
	v_lshrrev_b32_e32 v11, 16, v11
	v_add3_u32 v21, v21, v25, s14
	v_add3_u32 v20, v20, v24, s14
	v_and_or_b32 v11, v23, s15, v11
	v_and_or_b32 v10, v22, s15, v10
	ds_read_b64 v[22:23], v41 offset:64
	ds_read_b64 v[24:25], v41 offset:96
	v_lshrrev_b32_e32 v19, 16, v20
	v_lshrrev_b32_e32 v13, 16, v21
	v_pk_mul_f32 v[26:27], v[56:57], v[26:27]
	v_and_or_b32 v13, v12, s15, v13
	v_and_or_b32 v12, v18, s15, v19
	v_pk_mul_f32 v[36:37], v[64:65], v[36:37]
	v_pk_mul_f32 v[32:33], v[60:61], v[32:33]
	s_waitcnt lgkmcnt(2)
	v_mfma_f32_16x16x32_bf16 v[18:21], v[14:17], v[10:13], 0
	v_bfe_u32 v14, v27, 16, 1
	v_bfe_u32 v15, v26, 16, 1
	v_bfe_u32 v16, v53, 16, 1
	v_bfe_u32 v17, v52, 16, 1
	v_add3_u32 v46, v52, v17, s14
	v_add3_u32 v47, v53, v16, s14
	v_add3_u32 v15, v26, v15, s14
	v_add3_u32 v14, v27, v14, s14
	v_bfe_u32 v16, v50, 16, 1
	v_bfe_u32 v17, v51, 16, 1
	v_bfe_u32 v26, v28, 16, 1
	v_bfe_u32 v27, v29, 16, 1
	v_add3_u32 v27, v29, v27, s14
	v_add3_u32 v26, v28, v26, s14
	v_add3_u32 v17, v51, v17, s14
	v_add3_u32 v16, v50, v16, s14
	v_lshrrev_b32_e32 v28, 16, v16
	v_lshrrev_b32_e32 v29, 16, v17
	v_lshrrev_b32_e32 v16, 16, v26
	v_lshrrev_b32_e32 v17, 16, v27
	v_and_or_b32 v17, v14, s15, v17
	v_and_or_b32 v16, v15, s15, v16
	v_and_or_b32 v15, v47, s15, v29
	v_and_or_b32 v14, v46, s15, v28
	ds_read_b64 v[26:27], v41 offset:128
	ds_read_b64 v[28:29], v41 offset:160
	v_pk_mul_f32 v[30:31], v[62:63], v[30:31]
	s_waitcnt lgkmcnt(2)
	v_mfma_f32_16x16x32_bf16 v[18:21], v[22:25], v[14:17], v[18:21]
	v_bfe_u32 v22, v37, 16, 1
	v_bfe_u32 v23, v36, 16, 1
	v_bfe_u32 v24, v33, 16, 1
	v_bfe_u32 v25, v32, 16, 1
	v_add3_u32 v32, v32, v25, s14
	v_add3_u32 v33, v33, v24, s14
	v_add3_u32 v23, v36, v23, s14
	v_add3_u32 v22, v37, v22, s14
	v_bfe_u32 v24, v58, 16, 1
	v_bfe_u32 v25, v59, 16, 1
	v_bfe_u32 v36, v30, 16, 1
	v_bfe_u32 v37, v31, 16, 1
	v_add3_u32 v31, v31, v37, s14
	v_add3_u32 v30, v30, v36, s14
	v_add3_u32 v25, v59, v25, s14
	v_add3_u32 v24, v58, v24, s14
	v_lshrrev_b32_e32 v36, 16, v24
	v_lshrrev_b32_e32 v37, 16, v25
	v_lshrrev_b32_e32 v24, 16, v30
	v_lshrrev_b32_e32 v25, 16, v31
	v_and_or_b32 v25, v22, s15, v25
	v_and_or_b32 v24, v23, s15, v24
	v_and_or_b32 v23, v33, s15, v37
	v_and_or_b32 v22, v32, s15, v36
	ds_read_b64 v[30:31], v41 offset:192
	ds_read_b64 v[32:33], v41 offset:224
	v_pk_mul_f32 v[68:69], v[68:69], v[82:83]
	v_pk_mul_f32 v[34:35], v[66:67], v[34:35]
	s_waitcnt lgkmcnt(2)
	v_mfma_f32_16x16x32_bf16 v[26:29], v[26:29], v[22:25], v[18:21]
	v_bfe_u32 v41, v42, 16, 1
	v_add3_u32 v41, v42, v41, s14
	v_add_u32_e32 v47, 0xb000, v39
	v_bfe_u32 v19, v44, 16, 1
	v_bfe_u32 v20, v69, 16, 1
	v_bfe_u32 v21, v68, 16, 1
	v_add3_u32 v36, v68, v21, s14
	v_add3_u32 v37, v69, v20, s14
	v_add3_u32 v19, v44, v19, s14
	v_bfe_u32 v20, v34, 16, 1
	v_bfe_u32 v21, v35, 16, 1
	v_bfe_u32 v44, v43, 16, 1
	v_bfe_u32 v18, v45, 16, 1
	v_add3_u32 v43, v43, v44, s14
	v_add3_u32 v21, v35, v21, s14
	v_add3_u32 v20, v34, v20, s14
	v_add3_u32 v18, v45, v18, s14
	v_lshrrev_b32_e32 v34, 16, v20
	v_lshrrev_b32_e32 v35, 16, v21
	v_lshrrev_b32_e32 v20, 16, v41
	v_lshrrev_b32_e32 v21, 16, v43
	v_and_or_b32 v21, v18, s15, v21
	v_and_or_b32 v20, v19, s15, v20
	v_and_or_b32 v19, v37, s15, v35
	v_and_or_b32 v18, v36, s15, v34
	s_waitcnt lgkmcnt(0)
	s_nop 0
	v_mfma_f32_16x16x32_bf16 v[26:29], v[30:33], v[18:21], v[26:29]
	v_mul_u32_u24_e32 v30, 0x48, v71
	v_lshlrev_b32_e32 v30, 1, v30
	v_add3_u32 v41, s6, v72, v30
	v_add3_u32 v46, s24, v72, v30
	ds_read_b128 v[30:33], v41
	ds_read_b128 v[34:37], v46
	s_waitcnt lgkmcnt(1)
; #define MFMA16(a, b, c) __builtin_amdgcn_mfma_f32_16x16x32_bf16(a, b, c, 0, 0, 0)
; __device__ __forceinline__ void ret2_task(const Params& p_, int l, int task, unsigned char* lds) {
;     ...
;     for (int et = 0; et < 4; ++et) { f32x4 o = {0.f, 0.f, 0.f, 0.f}, cfa = o, cba = o;
; #pragma unroll
;         for (int t = 0; t < 4; ++t) { const u32x2 vlo = *(const u32x2*)(VT + (16 * et + fr) * 136 + 32 * t + 4 * fq), vhi = *(const u32x2*)(VT + (16 * et + fr) * 136 + 32 * t + 16 + 4 * fq);
;             o = MFMA16(mk8(vlo.x, vlo.y, vhi.x, vhi.y), mk8(pp[2 * t][0], pp[2 * t][1], pp[2 * t + 1][0], pp[2 * t + 1][1]), o); }
; #pragma unroll
;         for (int ks = 0; ks < 2; ++ks) { const bf16x8v sf = *(const bf16x8v*)(STF + (16 * et + fr) * 72 + 32 * ks + 8 * fq), sb = *(const bf16x8v*)(STB + (16 * et + fr) * 72 + 32 * ks + 8 * fq);
;             cfa = MFMA16(sf, qf[ks], cfa); cba = MFMA16(sb, qf[ks], cba); }
;         tot[et] = o + cfa * qdf + cba * qdb;
;         ss += (tot[et][0] * tot[et][0] + tot[et][1] * tot[et][1]) + (tot[et][2] * tot[et][2] + tot[et][3] * tot[et][3]); }
	v_mfma_f32_16x16x32_bf16 v[30:33], v[30:33], v[6:9], 0
	ds_read_b128 v[42:45], v41 offset:64
	ds_read_b128 v[48:51], v46 offset:64
	s_or_b32 s6, s43, s42
	s_lshl_b32 s24, s44, 1
	s_waitcnt lgkmcnt(2)
	v_mfma_f32_16x16x32_bf16 v[34:37], v[34:37], v[6:9], 0
	s_cmpk_lt_i32 s10, 0x200
	s_waitcnt lgkmcnt(1)
	v_mfma_f32_16x16x32_bf16 v[30:33], v[42:45], v[2:5], v[30:33]
	s_waitcnt lgkmcnt(0)
	v_mfma_f32_16x16x32_bf16 v[42:45], v[48:51], v[2:5], v[34:37]
	s_nop 5
	v_fma_f32 v28, v38, v32, v28
	v_fma_f32 v29, v38, v33, v29
	v_pk_fma_f32 v[26:27], v[38:39], v[30:31], v[26:27] op_sel_hi:[0,1,1]
	v_pk_fma_f32 v[34:35], v[40:41], v[44:45], v[28:29] op_sel_hi:[0,1,1]
	v_pk_fma_f32 v[36:37], v[40:41], v[42:43], v[26:27] op_sel_hi:[0,1,1]
	v_pk_mul_f32 v[26:27], v[34:35], v[34:35]
	v_pk_mul_f32 v[28:29], v[36:37], v[36:37]
	v_add_u32_e32 v44, 0xa000, v39
	v_pk_mov_b32 v[30:31], v[28:29], v[26:27] op_sel:[1,0]
	v_mov_b32_e32 v29, v27
	v_pk_add_f32 v[42:43], v[30:31], v[28:29]
	ds_read_b64 v[26:27], v44 offset:256
	ds_read_b64 v[28:29], v44 offset:288
	ds_read_b64 v[30:31], v44 offset:320
	ds_read_b64 v[32:33], v44 offset:352
	s_waitcnt lgkmcnt(2)
	v_mfma_f32_16x16x32_bf16 v[26:29], v[26:29], v[10:13], 0
	s_waitcnt lgkmcnt(0)
	v_mfma_f32_16x16x32_bf16 v[26:29], v[30:33], v[14:17], v[26:29]
	ds_read_b64 v[30:31], v44 offset:384
	ds_read_b64 v[32:33], v44 offset:416
	s_waitcnt lgkmcnt(0)
	v_mfma_f32_16x16x32_bf16 v[26:29], v[30:33], v[22:25], v[26:29]
	ds_read_b64 v[30:31], v44 offset:448
	ds_read_b64 v[32:33], v44 offset:480
	s_waitcnt lgkmcnt(0)
	v_mfma_f32_16x16x32_bf16 v[26:29], v[30:33], v[18:21], v[26:29]
	ds_read_b128 v[30:33], v41 offset:2304
	ds_read_b128 v[48:51], v46 offset:2304
	ds_read_b128 v[52:55], v41 offset:2368
	ds_read_b128 v[56:59], v46 offset:2368
	s_waitcnt lgkmcnt(3)
	v_mfma_f32_16x16x32_bf16 v[30:33], v[30:33], v[6:9], 0
	s_waitcnt lgkmcnt(2)
	v_mfma_f32_16x16x32_bf16 v[48:51], v[48:51], v[6:9], 0
	s_waitcnt lgkmcnt(1)
	v_mfma_f32_16x16x32_bf16 v[30:33], v[52:55], v[2:5], v[30:33]
	s_waitcnt lgkmcnt(0)
	v_mfma_f32_16x16x32_bf16 v[48:51], v[56:59], v[2:5], v[48:51]
	s_nop 5
	v_fma_f32 v28, v38, v32, v28
	v_fma_f32 v29, v38, v33, v29
	v_pk_fma_f32 v[26:27], v[38:39], v[30:31], v[26:27] op_sel_hi:[0,1,1]
	v_pk_fma_f32 v[30:31], v[40:41], v[50:51], v[28:29] op_sel_hi:[0,1,1]
	v_pk_fma_f32 v[32:33], v[40:41], v[48:49], v[26:27] op_sel_hi:[0,1,1]
	v_pk_mul_f32 v[26:27], v[30:31], v[30:31]
	v_pk_mul_f32 v[28:29], v[32:33], v[32:33]
	ds_read_b64 v[48:49], v47 offset:576
	ds_read_b64 v[50:51], v47 offset:608
	v_pk_mov_b32 v[44:45], v[28:29], v[26:27] op_sel:[1,0]
	v_mov_b32_e32 v29, v27
	v_pk_add_f32 v[44:45], v[44:45], v[28:29]
	ds_read_b64 v[26:27], v47 offset:512
	ds_read_b64 v[28:29], v47 offset:544
	s_waitcnt lgkmcnt(0)
	v_mfma_f32_16x16x32_bf16 v[26:29], v[26:29], v[10:13], 0
	v_mfma_f32_16x16x32_bf16 v[26:29], v[48:51], v[14:17], v[26:29]
	ds_read_b64 v[48:49], v47 offset:640
	ds_read_b64 v[50:51], v47 offset:672
	s_waitcnt lgkmcnt(0)
	v_mfma_f32_16x16x32_bf16 v[26:29], v[48:51], v[22:25], v[26:29]
	ds_read_b64 v[48:49], v47 offset:704
	ds_read_b64 v[50:51], v47 offset:736
	s_waitcnt lgkmcnt(0)
	v_mfma_f32_16x16x32_bf16 v[26:29], v[48:51], v[18:21], v[26:29]
	ds_read_b128 v[48:51], v41 offset:4608
	ds_read_b128 v[52:55], v46 offset:4608
	ds_read_b128 v[56:59], v41 offset:4672
	ds_read_b128 v[60:63], v46 offset:4672
	s_waitcnt lgkmcnt(3)
	v_mfma_f32_16x16x32_bf16 v[48:51], v[48:51], v[6:9], 0
	s_waitcnt lgkmcnt(2)
	v_mfma_f32_16x16x32_bf16 v[52:55], v[52:55], v[6:9], 0
	s_waitcnt lgkmcnt(1)
	v_mfma_f32_16x16x32_bf16 v[48:51], v[56:59], v[2:5], v[48:51]
	s_waitcnt lgkmcnt(0)
	v_mfma_f32_16x16x32_bf16 v[52:55], v[60:63], v[2:5], v[52:55]
	s_nop 5
	v_fma_f32 v28, v38, v50, v28
	v_fma_f32 v29, v38, v51, v29
	v_pk_fma_f32 v[48:49], v[38:39], v[48:49], v[26:27] op_sel_hi:[0,1,1]
	v_add_u32_e32 v39, 0xc000, v39
	v_pk_fma_f32 v[26:27], v[40:41], v[54:55], v[28:29] op_sel_hi:[0,1,1]
	v_pk_fma_f32 v[28:29], v[40:41], v[52:53], v[48:49] op_sel_hi:[0,1,1]
	ds_read_b64 v[48:49], v39 offset:768
	ds_read_b64 v[50:51], v39 offset:800
	s_waitcnt lgkmcnt(0)
	v_mfma_f32_16x16x32_bf16 v[10:13], v[48:51], v[10:13], 0
	ds_read_b64 v[48:49], v39 offset:832
	ds_read_b64 v[50:51], v39 offset:864
	s_waitcnt lgkmcnt(0)
	v_mfma_f32_16x16x32_bf16 v[10:13], v[48:51], v[14:17], v[10:13]
	ds_read_b64 v[14:15], v39 offset:896
	ds_read_b64 v[16:17], v39 offset:928
	s_waitcnt lgkmcnt(0)
	v_mfma_f32_16x16x32_bf16 v[10:13], v[14:17], v[22:25], v[10:13]
	ds_read_b64 v[14:15], v39 offset:960
	ds_read_b64 v[16:17], v39 offset:992
	s_waitcnt lgkmcnt(0)
	v_mfma_f32_16x16x32_bf16 v[10:13], v[14:17], v[18:21], v[10:13]
	ds_read_b128 v[14:17], v41 offset:6912
	ds_read_b128 v[18:21], v46 offset:6912
	s_waitcnt lgkmcnt(1)
	v_mfma_f32_16x16x32_bf16 v[14:17], v[14:17], v[6:9], 0
	s_waitcnt lgkmcnt(0)
	v_mfma_f32_16x16x32_bf16 v[6:9], v[18:21], v[6:9], 0
	ds_read_b128 v[18:21], v41 offset:6976
	ds_read_b128 v[22:25], v46 offset:6976
	s_waitcnt lgkmcnt(1)
	v_mfma_f32_16x16x32_bf16 v[14:17], v[18:21], v[2:5], v[14:17]
	v_mov_b32_e32 v18, v36
	v_mov_b32_e32 v19, v34
	v_mov_b32_e32 v34, v37
	s_waitcnt lgkmcnt(0)
; __device__ __forceinline__ unsigned pk2(float lo, float hi) { return f2bf(lo) | (f2bf(hi) << 16); }
; __device__ __forceinline__ float bflo(unsigned u) { return __uint_as_float(u << 16); }
; __device__ __forceinline__ float bfhi(unsigned u) { return __uint_as_float(u & 0xffff0000u); }
; __device__ __forceinline__ float silu_f(float v) { return v / (1.f + __expf(-v)); }
; __device__ __forceinline__ void ret2_task(const Params& p_, int l, int task, unsigned char* lds) {
;     ...
;         tot[et] = o + cfa * qdf + cba * qdb;
;         ss += (tot[et][0] * tot[et][0] + tot[et][1] * tot[et][1]) + (tot[et][2] * tot[et][2] + tot[et][3] * tot[et][3]); }
;     ss += __shfl_xor(ss, 16); ss += __shfl_xor(ss, 32);
;     const float rs = rsqrtf(ss * (1.f / 64.f) + 1e-6f);
;     const size_t tok = (size_t)b * SEQ + n * 128 + ai;
;     const bf16* Z = (const bf16*)(p.ws + WS_Z); bf16* CAT = (bf16*)(p.ws + WS_CAT);
; #pragma unroll
;     for (int et = 0; et < 4; ++et) { const u32x2 gz = *(const u32x2*)(Z + tok * DIN + 9 * DG + h * 64 + 16 * et + 4 * fq); u32x2 o;
;         o.x = pk2(tot[et][0] * rs * silu_f(bflo(gz.x)), tot[et][1] * rs * silu_f(bfhi(gz.x))); o.y = pk2(tot[et][2] * rs * silu_f(bflo(gz.y)), tot[et][3] * rs * silu_f(bfhi(gz.y)));
;         *(u32x2*)(CAT + tok * DM + 1024 + h * 64 + 16 * et + 4 * fq) = o; }
	v_mfma_f32_16x16x32_bf16 v[4:7], v[22:25], v[2:5], v[6:9]
	s_nop 2
	v_fma_f32 v2, v38, v16, v12
	v_fma_f32 v3, v38, v17, v13
	v_pk_fma_f32 v[8:9], v[38:39], v[14:15], v[10:11] op_sel_hi:[0,1,1]
	s_nop 1
	v_pk_fma_f32 v[4:5], v[40:41], v[4:5], v[8:9] op_sel_hi:[0,1,1]
	v_pk_fma_f32 v[2:3], v[40:41], v[6:7], v[2:3] op_sel_hi:[0,1,1]
	v_mul_f32_e32 v8, v4, v4
	v_pk_add_f32 v[6:7], v[42:43], v[42:43] op_sel:[0,1] op_sel_hi:[1,0]
	v_mul_f32_e32 v10, v5, v5
	v_mov_b32_e32 v7, v8
	v_pk_add_f32 v[8:9], v[44:45], v[44:45] op_sel:[0,1] op_sel_hi:[1,0]
	v_mul_f32_e32 v11, v2, v2
	v_mov_b32_e32 v9, v10
	v_pk_add_f32 v[6:7], v[6:7], v[8:9]
	v_mul_f32_e32 v8, v29, v29
	v_pk_fma_f32 v[8:9], v[28:29], v[28:29], v[8:9] op_sel_hi:[1,1,0]
	v_mul_f32_e32 v10, v27, v27
	v_mul_f32_e32 v12, v3, v3
	v_mov_b32_e32 v9, v11
	v_pk_fma_f32 v[10:11], v[26:27], v[26:27], v[10:11] op_sel_hi:[1,1,0]
	s_nop 0
	v_mov_b32_e32 v11, v12
	v_pk_add_f32 v[8:9], v[8:9], v[10:11]
	s_nop 0
	v_pk_add_f32 v[6:7], v[6:7], v[8:9]
	v_and_b32_e32 v8, 64, v178
	v_add_f32_e32 v6, v6, v7
	v_xor_b32_e32 v7, 16, v178
	v_add_u32_e32 v8, 64, v8
	v_cmp_lt_i32_e32 vcc, v7, v8
	s_nop 1
	v_cndmask_b32_e32 v7, v178, v7, vcc
	v_lshlrev_b32_e32 v7, 2, v7
	ds_bpermute_b32 v7, v7, v6
	s_waitcnt lgkmcnt(0)
	v_add_f32_e32 v6, v6, v7
	v_xor_b32_e32 v7, 32, v178
	v_cmp_lt_i32_e32 vcc, v7, v8
	v_mov_b64_e32 v[8:9], s[36:37]
	s_nop 0
	v_cndmask_b32_e32 v7, v178, v7, vcc
	v_lshlrev_b32_e32 v7, 2, v7
	ds_bpermute_b32 v7, v7, v6
	s_waitcnt lgkmcnt(0)
	v_add_f32_e32 v6, v6, v7
	v_fmamk_f32 v6, v6, 0x3c800000, v146
	v_cmp_gt_f32_e32 vcc, s92, v6
	v_mul_f32_e32 v7, 0x4b800000, v6
	s_nop 0
	v_cndmask_b32_e32 v6, v6, v7, vcc
	v_rsq_f32_e32 v6, v6
	s_nop 0
	v_mul_f32_e32 v7, 0x45800000, v6
	v_cndmask_b32_e32 v6, v6, v7, vcc
	v_add_u32_e32 v7, s6, v70
	v_mad_i64_i32 v[8:9], s[12:13], v7, s75, v[8:9]
	v_lshl_add_u64 v[10:11], v[8:9], 0, s[24:25]
	v_lshl_add_u64 v[12:13], v[10:11], 0, v[0:1]
	s_mov_b64 s[12:13], 0xad22400
	s_movk_i32 s6, 0xdc00
	v_lshl_add_u64 v[10:11], v[12:13], 0, s[12:13]
	v_mad_i64_i32 v[8:9], s[12:13], v7, s6, v[8:9]
	s_mov_b32 s6, 0xad22000
	v_add_co_u32_e32 v12, vcc, s6, v12
	v_lshl_add_u64 v[8:9], v[8:9], 0, s[24:25]
	s_nop 0
	v_addc_co_u32_e32 v13, vcc, 0, v13, vcc
	global_load_dwordx2 v[84:85], v[10:11], off offset:32
	global_load_dwordx2 v[86:87], v[10:11], off offset:64
	global_load_dwordx2 v[88:89], v[10:11], off offset:96
	global_load_dwordx2 v[12:13], v[12:13], off offset:1024
	v_lshl_add_u64 v[14:15], v[8:9], 0, v[0:1]
	s_mov_b64 s[12:13], 0x12d20800
	v_lshl_add_u64 v[8:9], v[14:15], 0, s[12:13]
	s_mov_b32 s6, 0x12d20000
	s_waitcnt vmcnt(0)
	v_lshlrev_b32_e32 v0, 16, v13
	v_lshlrev_b32_e32 v7, 16, v12
	v_mul_f32_e32 v16, 0xbfb8aa3b, v7
	v_and_b32_e32 v20, 0xffff0000, v13
	v_mul_f32_e32 v13, 0xbfb8aa3b, v0
	v_exp_f32_e32 v16, v16
	v_exp_f32_e32 v17, v13
	v_and_b32_e32 v21, 0xffff0000, v12
	v_mul_f32_e32 v12, 0xbfb8aa3b, v21
	v_exp_f32_e32 v12, v12
	v_pk_add_f32 v[16:17], v[16:17], 1.0 op_sel_hi:[1,0]
	v_pk_mul_f32 v[18:19], v[18:19], v[6:7] op_sel_hi:[1,0]
	v_div_scale_f32 v13, s[12:13], v17, v17, v0
	v_rcp_f32_e32 v22, v13
	s_nop 0
	v_fma_f32 v23, -v13, v22, 1.0
	v_fmac_f32_e32 v22, v23, v22
	v_div_scale_f32 v23, vcc, v0, v17, v0
	v_mul_f32_e32 v24, v23, v22
	v_fma_f32 v25, -v13, v24, v23
	v_fmac_f32_e32 v24, v25, v22
	v_fma_f32 v13, -v13, v24, v23
	v_div_fmas_f32 v13, v13, v22, v24
	v_div_fixup_f32 v17, v13, v17, v0
	v_div_scale_f32 v0, s[12:13], v16, v16, v7
	v_rcp_f32_e32 v13, v0
	s_nop 0
	v_fma_f32 v22, -v0, v13, 1.0
	v_fmac_f32_e32 v13, v22, v13
	v_div_scale_f32 v22, vcc, v7, v16, v7
	v_mul_f32_e32 v23, v22, v13
	v_fma_f32 v24, -v0, v23, v22
	v_fmac_f32_e32 v23, v24, v13
	v_fma_f32 v0, -v0, v23, v22
	v_div_fmas_f32 v0, v0, v13, v23
	v_div_fixup_f32 v16, v0, v16, v7
	v_mul_f32_e32 v0, 0xbfb8aa3b, v20
	v_exp_f32_e32 v13, v0
	v_pk_mul_f32 v[16:17], v[16:17], v[18:19]
	v_pk_mul_f32 v[18:19], v[34:35], v[6:7] op_sel_hi:[1,0]
	v_pk_add_f32 v[12:13], v[12:13], 1.0 op_sel_hi:[1,0]
	s_nop 0
	v_div_scale_f32 v0, s[12:13], v13, v13, v20
	v_rcp_f32_e32 v7, v0
	s_nop 0
	v_fma_f32 v22, -v0, v7, 1.0
	v_fmac_f32_e32 v7, v22, v7
	v_div_scale_f32 v22, vcc, v20, v13, v20
	v_mul_f32_e32 v23, v22, v7
	v_fma_f32 v24, -v0, v23, v22
	v_fmac_f32_e32 v23, v24, v7
	v_fma_f32 v0, -v0, v23, v22
	v_div_fmas_f32 v0, v0, v7, v23
	v_div_fixup_f32 v13, v0, v13, v20
	v_div_scale_f32 v0, s[12:13], v12, v12, v21
	v_rcp_f32_e32 v7, v0
	s_nop 0
	v_fma_f32 v20, -v0, v7, 1.0
	v_fmac_f32_e32 v7, v20, v7
	v_div_scale_f32 v20, vcc, v21, v12, v21
	v_mul_f32_e32 v22, v20, v7
	v_fma_f32 v23, -v0, v22, v20
	v_fmac_f32_e32 v22, v23, v7
	v_fma_f32 v0, -v0, v22, v20
	v_div_fmas_f32 v0, v0, v7, v22
	v_div_fixup_f32 v12, v0, v12, v21
	v_pk_mul_f32 v[12:13], v[12:13], v[18:19]
	v_and_b32_sdwa v0, v17, v179 dst_sel:DWORD dst_unused:UNUSED_PAD src0_sel:WORD_1 src1_sel:DWORD
	v_and_b32_sdwa v7, v16, v179 dst_sel:DWORD dst_unused:UNUSED_PAD src0_sel:WORD_1 src1_sel:DWORD
	v_add3_u32 v7, v16, v7, s14
	v_add3_u32 v0, v17, v0, s14
	v_and_b32_sdwa v16, v13, v179 dst_sel:DWORD dst_unused:UNUSED_PAD src0_sel:WORD_1 src1_sel:DWORD
	v_and_b32_sdwa v17, v12, v179 dst_sel:DWORD dst_unused:UNUSED_PAD src0_sel:WORD_1 src1_sel:DWORD
	v_add3_u32 v13, v13, v16, s14
	v_add3_u32 v12, v12, v17, s14
	v_and_b32_e32 v13, 0xffff0000, v13
	v_and_b32_e32 v12, 0xffff0000, v12
	v_add_co_u32_e32 v14, vcc, s6, v14
	v_or_b32_sdwa v13, v13, v0 dst_sel:DWORD dst_unused:UNUSED_PAD src0_sel:DWORD src1_sel:WORD_1
	v_or_b32_sdwa v12, v12, v7 dst_sel:DWORD dst_unused:UNUSED_PAD src0_sel:DWORD src1_sel:WORD_1
	v_addc_co_u32_e32 v15, vcc, 0, v15, vcc
; __device__ __forceinline__ unsigned pk2(float lo, float hi) { return f2bf(lo) | (f2bf(hi) << 16); }
; __device__ __forceinline__ float bflo(unsigned u) { return __uint_as_float(u << 16); }
; __device__ __forceinline__ float bfhi(unsigned u) { return __uint_as_float(u & 0xffff0000u); }
; __device__ __forceinline__ float silu_f(float v) { return v / (1.f + __expf(-v)); }
; __device__ __forceinline__ void ret2_task(const Params& p_, int l, int task, unsigned char* lds) {
;     ...
;     for (int et = 0; et < 4; ++et) { const u32x2 gz = *(const u32x2*)(Z + tok * DIN + 9 * DG + h * 64 + 16 * et + 4 * fq); u32x2 o;
;         o.x = pk2(tot[et][0] * rs * silu_f(bflo(gz.x)), tot[et][1] * rs * silu_f(bfhi(gz.x))); o.y = pk2(tot[et][2] * rs * silu_f(bflo(gz.y)), tot[et][3] * rs * silu_f(bfhi(gz.y)));
;         *(u32x2*)(CAT + tok * DM + 1024 + h * 64 + 16 * et + 4 * fq) = o; }
	global_store_dwordx2 v[14:15], v[12:13], off offset:2048
	v_mov_b64_e32 v[12:13], v[84:85]
	v_mov_b32_e32 v16, v32
	v_mov_b32_e32 v17, v30
	v_mov_b32_e32 v30, v33
	s_nop 0
	v_lshlrev_b32_e32 v0, 16, v13
	v_lshlrev_b32_e32 v7, 16, v12
	v_mul_f32_e32 v14, 0xbfb8aa3b, v7
	v_and_b32_e32 v18, 0xffff0000, v13
	v_mul_f32_e32 v13, 0xbfb8aa3b, v0
	v_exp_f32_e32 v14, v14
	v_exp_f32_e32 v15, v13
	v_and_b32_e32 v19, 0xffff0000, v12
	v_mul_f32_e32 v12, 0xbfb8aa3b, v19
	v_exp_f32_e32 v12, v12
	v_pk_add_f32 v[14:15], v[14:15], 1.0 op_sel_hi:[1,0]
	v_pk_mul_f32 v[16:17], v[16:17], v[6:7] op_sel_hi:[1,0]
	v_div_scale_f32 v13, s[12:13], v15, v15, v0
	v_rcp_f32_e32 v20, v13
	s_nop 0
	v_fma_f32 v21, -v13, v20, 1.0
	v_fmac_f32_e32 v20, v21, v20
	v_div_scale_f32 v21, vcc, v0, v15, v0
	v_mul_f32_e32 v22, v21, v20
	v_fma_f32 v23, -v13, v22, v21
	v_fmac_f32_e32 v22, v23, v20
	v_fma_f32 v13, -v13, v22, v21
	v_div_fmas_f32 v13, v13, v20, v22
	v_div_fixup_f32 v15, v13, v15, v0
	v_div_scale_f32 v0, s[12:13], v14, v14, v7
	v_rcp_f32_e32 v13, v0
	s_nop 0
	v_fma_f32 v20, -v0, v13, 1.0
	v_fmac_f32_e32 v13, v20, v13
	v_div_scale_f32 v20, vcc, v7, v14, v7
	v_mul_f32_e32 v21, v20, v13
	v_fma_f32 v22, -v0, v21, v20
	v_fmac_f32_e32 v21, v22, v13
	v_fma_f32 v0, -v0, v21, v20
	v_div_fmas_f32 v0, v0, v13, v21
	v_div_fixup_f32 v14, v0, v14, v7
	v_mul_f32_e32 v0, 0xbfb8aa3b, v18
	v_exp_f32_e32 v13, v0
	v_pk_mul_f32 v[14:15], v[14:15], v[16:17]
	v_pk_mul_f32 v[16:17], v[30:31], v[6:7] op_sel_hi:[1,0]
	v_pk_add_f32 v[12:13], v[12:13], 1.0 op_sel_hi:[1,0]
	s_nop 0
	v_div_scale_f32 v0, s[12:13], v13, v13, v18
	v_rcp_f32_e32 v7, v0
	s_nop 0
	v_fma_f32 v20, -v0, v7, 1.0
	v_fmac_f32_e32 v7, v20, v7
	v_div_scale_f32 v20, vcc, v18, v13, v18
	v_mul_f32_e32 v21, v20, v7
	v_fma_f32 v22, -v0, v21, v20
	v_fmac_f32_e32 v21, v22, v7
	v_fma_f32 v0, -v0, v21, v20
	v_div_fmas_f32 v0, v0, v7, v21
	v_div_fixup_f32 v13, v0, v13, v18
	v_div_scale_f32 v0, s[12:13], v12, v12, v19
	v_rcp_f32_e32 v7, v0
	s_nop 0
	v_fma_f32 v18, -v0, v7, 1.0
	v_fmac_f32_e32 v7, v18, v7
	v_div_scale_f32 v18, vcc, v19, v12, v19
	v_mul_f32_e32 v20, v18, v7
	v_fma_f32 v21, -v0, v20, v18
	v_fmac_f32_e32 v20, v21, v7
	v_fma_f32 v0, -v0, v20, v18
	v_div_fmas_f32 v0, v0, v7, v20
	v_div_fixup_f32 v12, v0, v12, v19
	v_pk_mul_f32 v[12:13], v[12:13], v[16:17]
	v_and_b32_sdwa v0, v15, v179 dst_sel:DWORD dst_unused:UNUSED_PAD src0_sel:WORD_1 src1_sel:DWORD
	v_and_b32_sdwa v7, v14, v179 dst_sel:DWORD dst_unused:UNUSED_PAD src0_sel:WORD_1 src1_sel:DWORD
	v_add3_u32 v7, v14, v7, s14
	v_add3_u32 v0, v15, v0, s14
	v_and_b32_sdwa v14, v13, v179 dst_sel:DWORD dst_unused:UNUSED_PAD src0_sel:WORD_1 src1_sel:DWORD
	v_and_b32_sdwa v15, v12, v179 dst_sel:DWORD dst_unused:UNUSED_PAD src0_sel:WORD_1 src1_sel:DWORD
	v_add3_u32 v13, v13, v14, s14
	v_add3_u32 v12, v12, v15, s14
	v_and_b32_e32 v13, 0xffff0000, v13
	v_and_b32_e32 v12, 0xffff0000, v12
	v_or_b32_sdwa v13, v13, v0 dst_sel:DWORD dst_unused:UNUSED_PAD src0_sel:DWORD src1_sel:WORD_1
	v_or_b32_sdwa v12, v12, v7 dst_sel:DWORD dst_unused:UNUSED_PAD src0_sel:DWORD src1_sel:WORD_1
	global_store_dwordx2 v[8:9], v[12:13], off offset:32
	v_mov_b64_e32 v[12:13], v[86:87]
	v_mov_b32_e32 v16, v28
	v_mov_b64_e32 v[10:11], v[88:89]
	v_mov_b32_e32 v17, v26
	v_mov_b32_e32 v26, v29
	s_nop 0
	v_lshlrev_b32_e32 v0, 16, v13
	v_lshlrev_b32_e32 v7, 16, v12
	v_mul_f32_e32 v14, 0xbfb8aa3b, v7
	v_and_b32_e32 v18, 0xffff0000, v13
	v_mul_f32_e32 v13, 0xbfb8aa3b, v0
	v_exp_f32_e32 v14, v14
	v_exp_f32_e32 v15, v13
	v_and_b32_e32 v19, 0xffff0000, v12
	v_mul_f32_e32 v12, 0xbfb8aa3b, v19
	v_exp_f32_e32 v12, v12
	v_pk_add_f32 v[14:15], v[14:15], 1.0 op_sel_hi:[1,0]
	v_pk_mul_f32 v[16:17], v[16:17], v[6:7] op_sel_hi:[1,0]
	v_div_scale_f32 v13, s[12:13], v15, v15, v0
	v_rcp_f32_e32 v20, v13
	s_nop 0
	v_fma_f32 v21, -v13, v20, 1.0
	v_fmac_f32_e32 v20, v21, v20
	v_div_scale_f32 v21, vcc, v0, v15, v0
	v_mul_f32_e32 v22, v21, v20
	v_fma_f32 v23, -v13, v22, v21
	v_fmac_f32_e32 v22, v23, v20
	v_fma_f32 v13, -v13, v22, v21
	v_div_fmas_f32 v13, v13, v20, v22
	v_div_fixup_f32 v15, v13, v15, v0
	v_div_scale_f32 v0, s[12:13], v14, v14, v7
	v_rcp_f32_e32 v13, v0
	s_nop 0
	v_fma_f32 v20, -v0, v13, 1.0
	v_fmac_f32_e32 v13, v20, v13
	v_div_scale_f32 v20, vcc, v7, v14, v7
	v_mul_f32_e32 v21, v20, v13
	v_fma_f32 v22, -v0, v21, v20
	v_fmac_f32_e32 v21, v22, v13
	v_fma_f32 v0, -v0, v21, v20
	v_div_fmas_f32 v0, v0, v13, v21
	v_div_fixup_f32 v14, v0, v14, v7
	v_mul_f32_e32 v0, 0xbfb8aa3b, v18
	v_exp_f32_e32 v13, v0
	v_pk_mul_f32 v[14:15], v[14:15], v[16:17]
	v_pk_mul_f32 v[16:17], v[26:27], v[6:7] op_sel_hi:[1,0]
; __device__ __forceinline__ unsigned pk2(float lo, float hi) { return f2bf(lo) | (f2bf(hi) << 16); }
; __device__ __forceinline__ float bflo(unsigned u) { return __uint_as_float(u << 16); }
; __device__ __forceinline__ float bfhi(unsigned u) { return __uint_as_float(u & 0xffff0000u); }
; __device__ __forceinline__ float silu_f(float v) { return v / (1.f + __expf(-v)); }
; __device__ __forceinline__ void ret2_task(const Params& p_, int l, int task, unsigned char* lds) {
;     ...
;     for (int et = 0; et < 4; ++et) { const u32x2 gz = *(const u32x2*)(Z + tok * DIN + 9 * DG + h * 64 + 16 * et + 4 * fq); u32x2 o;
;         o.x = pk2(tot[et][0] * rs * silu_f(bflo(gz.x)), tot[et][1] * rs * silu_f(bfhi(gz.x))); o.y = pk2(tot[et][2] * rs * silu_f(bflo(gz.y)), tot[et][3] * rs * silu_f(bfhi(gz.y)));
;         *(u32x2*)(CAT + tok * DM + 1024 + h * 64 + 16 * et + 4 * fq) = o; }
;     __syncthreads();
	v_pk_add_f32 v[12:13], v[12:13], 1.0 op_sel_hi:[1,0]
	s_nop 0
	v_div_scale_f32 v0, s[12:13], v13, v13, v18
	v_rcp_f32_e32 v7, v0
	s_nop 0
	v_fma_f32 v20, -v0, v7, 1.0
	v_fmac_f32_e32 v7, v20, v7
	v_div_scale_f32 v20, vcc, v18, v13, v18
	v_mul_f32_e32 v21, v20, v7
	v_fma_f32 v22, -v0, v21, v20
	v_fmac_f32_e32 v21, v22, v7
	v_fma_f32 v0, -v0, v21, v20
	v_div_fmas_f32 v0, v0, v7, v21
	v_div_fixup_f32 v13, v0, v13, v18
	v_div_scale_f32 v0, s[12:13], v12, v12, v19
	v_rcp_f32_e32 v7, v0
	s_nop 0
	v_fma_f32 v18, -v0, v7, 1.0
	v_fmac_f32_e32 v7, v18, v7
	v_div_scale_f32 v18, vcc, v19, v12, v19
	v_mul_f32_e32 v20, v18, v7
	v_fma_f32 v21, -v0, v20, v18
	v_fmac_f32_e32 v20, v21, v7
	v_fma_f32 v0, -v0, v20, v18
	v_div_fmas_f32 v0, v0, v7, v20
	v_div_fixup_f32 v12, v0, v12, v19
	v_pk_mul_f32 v[12:13], v[12:13], v[16:17]
	v_and_b32_sdwa v0, v15, v179 dst_sel:DWORD dst_unused:UNUSED_PAD src0_sel:WORD_1 src1_sel:DWORD
	v_and_b32_sdwa v7, v14, v179 dst_sel:DWORD dst_unused:UNUSED_PAD src0_sel:WORD_1 src1_sel:DWORD
	v_add3_u32 v7, v14, v7, s14
	v_add3_u32 v0, v15, v0, s14
	v_and_b32_sdwa v14, v13, v179 dst_sel:DWORD dst_unused:UNUSED_PAD src0_sel:WORD_1 src1_sel:DWORD
	v_and_b32_sdwa v15, v12, v179 dst_sel:DWORD dst_unused:UNUSED_PAD src0_sel:WORD_1 src1_sel:DWORD
	v_add3_u32 v13, v13, v14, s14
	v_add3_u32 v12, v12, v15, s14
	v_and_b32_e32 v13, 0xffff0000, v13
	v_and_b32_e32 v12, 0xffff0000, v12
	v_or_b32_sdwa v13, v13, v0 dst_sel:DWORD dst_unused:UNUSED_PAD src0_sel:DWORD src1_sel:WORD_1
	v_or_b32_sdwa v12, v12, v7 dst_sel:DWORD dst_unused:UNUSED_PAD src0_sel:DWORD src1_sel:WORD_1
	s_nop 0
	v_lshlrev_b32_e32 v0, 16, v11
	v_lshlrev_b32_e32 v7, 16, v10
	global_store_dwordx2 v[8:9], v[12:13], off offset:64
	v_mul_f32_e32 v12, 0xbfb8aa3b, v7
	v_mov_b32_e32 v15, v2
	v_mul_f32_e32 v2, 0xbfb8aa3b, v0
	v_exp_f32_e32 v12, v12
	v_exp_f32_e32 v13, v2
	v_mov_b32_e32 v14, v4
	v_and_b32_e32 v16, 0xffff0000, v11
	v_and_b32_e32 v17, 0xffff0000, v10
	v_pk_add_f32 v[12:13], v[12:13], 1.0 op_sel_hi:[1,0]
	v_mul_f32_e32 v10, 0xbfb8aa3b, v17
	v_div_scale_f32 v2, s[12:13], v13, v13, v0
	v_rcp_f32_e32 v4, v2
	v_exp_f32_e32 v10, v10
	v_pk_mul_f32 v[14:15], v[14:15], v[6:7] op_sel_hi:[1,0]
	v_fma_f32 v11, -v2, v4, 1.0
	v_fmac_f32_e32 v4, v11, v4
	v_div_scale_f32 v11, vcc, v0, v13, v0
	v_mul_f32_e32 v18, v11, v4
	v_fma_f32 v19, -v2, v18, v11
	v_fmac_f32_e32 v18, v19, v4
	v_fma_f32 v2, -v2, v18, v11
	v_div_fmas_f32 v2, v2, v4, v18
	v_div_fixup_f32 v13, v2, v13, v0
	v_div_scale_f32 v0, s[12:13], v12, v12, v7
	v_rcp_f32_e32 v2, v0
	s_nop 0
	v_fma_f32 v4, -v0, v2, 1.0
	v_fmac_f32_e32 v2, v4, v2
	v_div_scale_f32 v4, vcc, v7, v12, v7
	v_mul_f32_e32 v11, v4, v2
	v_fma_f32 v18, -v0, v11, v4
	v_fmac_f32_e32 v11, v18, v2
	v_fma_f32 v0, -v0, v11, v4
	v_div_fmas_f32 v0, v0, v2, v11
	v_div_fixup_f32 v12, v0, v12, v7
	v_mul_f32_e32 v0, 0xbfb8aa3b, v16
	v_exp_f32_e32 v11, v0
	v_mov_b32_e32 v2, v5
	v_pk_mul_f32 v[2:3], v[2:3], v[6:7] op_sel_hi:[1,0]
	v_pk_mul_f32 v[12:13], v[14:15], v[12:13]
	v_pk_add_f32 v[4:5], v[10:11], 1.0 op_sel_hi:[1,0]
	s_nop 0
	v_div_scale_f32 v0, s[12:13], v5, v5, v16
	v_rcp_f32_e32 v6, v0
	s_nop 0
	v_fma_f32 v7, -v0, v6, 1.0
	v_fmac_f32_e32 v6, v7, v6
	v_div_scale_f32 v7, vcc, v16, v5, v16
	v_mul_f32_e32 v10, v7, v6
	v_fma_f32 v11, -v0, v10, v7
	v_fmac_f32_e32 v10, v11, v6
	v_fma_f32 v0, -v0, v10, v7
	v_div_fmas_f32 v0, v0, v6, v10
	v_div_fixup_f32 v5, v0, v5, v16
	v_div_scale_f32 v0, s[12:13], v4, v4, v17
	v_rcp_f32_e32 v6, v0
	s_nop 0
	v_fma_f32 v7, -v0, v6, 1.0
	v_fmac_f32_e32 v6, v7, v6
	v_div_scale_f32 v7, vcc, v17, v4, v17
	v_mul_f32_e32 v10, v7, v6
	v_fma_f32 v11, -v0, v10, v7
	v_fmac_f32_e32 v10, v11, v6
	v_fma_f32 v0, -v0, v10, v7
	v_div_fmas_f32 v0, v0, v6, v10
	v_div_fixup_f32 v4, v0, v4, v17
	v_pk_mul_f32 v[2:3], v[2:3], v[4:5]
	v_and_b32_sdwa v0, v13, v179 dst_sel:DWORD dst_unused:UNUSED_PAD src0_sel:WORD_1 src1_sel:DWORD
	v_and_b32_sdwa v5, v3, v179 dst_sel:DWORD dst_unused:UNUSED_PAD src0_sel:WORD_1 src1_sel:DWORD
	v_and_b32_sdwa v6, v2, v179 dst_sel:DWORD dst_unused:UNUSED_PAD src0_sel:WORD_1 src1_sel:DWORD
	v_and_b32_sdwa v4, v12, v179 dst_sel:DWORD dst_unused:UNUSED_PAD src0_sel:WORD_1 src1_sel:DWORD
	v_add3_u32 v3, v3, v5, s14
	v_add3_u32 v2, v2, v6, s14
	v_add3_u32 v4, v12, v4, s14
	v_add3_u32 v0, v13, v0, s14
	v_and_b32_e32 v3, 0xffff0000, v3
	v_and_b32_e32 v2, 0xffff0000, v2
	v_or_b32_sdwa v3, v3, v0 dst_sel:DWORD dst_unused:UNUSED_PAD src0_sel:DWORD src1_sel:WORD_1
	v_or_b32_sdwa v2, v2, v4 dst_sel:DWORD dst_unused:UNUSED_PAD src0_sel:DWORD src1_sel:WORD_1
	global_store_dwordx2 v[8:9], v[2:3], off offset:96
	s_barrier
	s_cbranch_scc0 .LBB0_577
